# final_norm loop: loop-invariant gain vector loaded once before the loop, per-load full waits removed
# baseline (speedup 1.0000x reference)
; __device__ __forceinline__ float* kout() { return (float*)kin(29); }
; __device__ __forceinline__ float wave_sum(float v) { v = row16_allsum(v); v = rows_pair_sum(v); v = halves_pair_sum(v); return v; }
; __device__ __forceinline__ void final_norm(const Params& P, int gw, int NGW, int lane) {
;     ...
;     for (int m0 = 2 * gw; m0 < T; m0 += 2 * NGW) {
;         f32x4 v[2][4]; float s[2] = {0.f, 0.f};
; #pragma unroll
;         for (int q = 0; q < 2; ++q) { const f32x4* xr = (const f32x4*)(kout() + (size_t)(m0 + q) * D) + lane;
; #pragma unroll
;             for (int j = 0; j < 4; ++j) v[q][j] = xr[64 * j]; }
; #pragma unroll
;         for (int q = 0; q < 2; ++q) {
; #pragma unroll
;             for (int j = 0; j < 4; ++j) s[q] += (v[q][j].x * v[q][j].x + v[q][j].y * v[q][j].y) + (v[q][j].z * v[q][j].z + v[q][j].w * v[q][j].w); }
; #pragma unroll
;         for (int q = 0; q < 2; ++q) {
;             f32x4* xr = (f32x4*)(kout() + (size_t)(m0 + q) * D) + lane;
;             const float rstd = 1.0f / sqrtf(wave_sum(s[q]) * (1.0f / D) + 1e-6f);
; #pragma unroll
;             for (int j = 0; j < 4; ++j) { const f32x4 gg = ((const f32x4*)g)[lane + 64 * j]; xr[64 * j] = v[q][j] * rstd * gg; }
.LBB0_1106:
	v_readlane_b32 s2, v255, 16
	v_ashrrev_i32_e32 v0, 6, v203
	s_movk_i32 s4, 0x2000
	v_add_u32_e32 v0, s2, v0
	s_mov_b64 s[2:3], s[0:1]
	v_cmp_gt_i32_e32 vcc, s4, v0
	s_and_saveexec_b64 s[4:5], vcc
	v_readlane_b32 s12, v255, 31
	v_readlane_b32 s13, v255, 32
	s_cbranch_execz .LBB0_1109
	s_load_dwordx2 s[2:3], s[2:3], 0xe0
	v_lshlrev_b32_e32 v20, 1, v0
	v_lshlrev_b32_e32 v0, 4, v203
	v_mov_b32_e32 v1, 0
	v_and_b32_e32 v0, 0x3f0, v0
	v_ashrrev_i32_e32 v21, 31, v20
	s_waitcnt lgkmcnt(0)
	v_lshl_add_u64 v[22:23], s[2:3], 0, v[0:1]
	v_lshlrev_b64 v[24:25], 12, v[20:21]
	s_movk_i32 s2, 0x1c00
	v_or3_b32 v24, v24, v0, s2
	s_mov_b64 s[4:5], 0
	s_movk_i32 s8, 0xf000
	v_mov_b32_e32 v21, 0x358637bd
	s_mov_b32 s9, 0xf800000
	v_mov_b32_e32 v26, 0x260
	s_movk_i32 s10, 0x3fff
	global_load_dwordx4 v[60:63], v[22:23], off
	global_load_dwordx4 v[64:67], v[22:23], off offset:1024
	global_load_dwordx4 v[68:71], v[22:23], off offset:2048
	global_load_dwordx4 v[72:75], v[22:23], off offset:3072
.LBB0_1108:
	s_mov_b64 s[2:3], s[0:1]
	s_load_dwordx2 s[2:3], s[2:3], 0xe8
	s_mov_b64 s[6:7], s[0:1]
	v_add_u32_e32 v20, s66, v20
	s_waitcnt lgkmcnt(0)
	v_lshl_add_u64 v[0:1], s[2:3], 0, v[24:25]
	v_add_co_u32_e32 v2, vcc, 0xfffff000, v0
	s_mov_b64 s[2:3], s[0:1]
	s_nop 0
	v_addc_co_u32_e32 v3, vcc, -1, v1, vcc
	global_load_dwordx4 v[28:31], v[2:3], off offset:-3072
	global_load_dwordx4 v[32:35], v[2:3], off offset:-2048
	global_load_dwordx4 v[36:39], v[2:3], off offset:-1024
	global_load_dwordx4 v[16:19], v[0:1], off offset:-4096
	s_load_dwordx2 s[2:3], s[2:3], 0xe8
	s_waitcnt lgkmcnt(0)
	v_lshl_add_u64 v[40:41], s[2:3], 0, v[24:25]
	global_load_dwordx4 v[12:15], v[40:41], off offset:-3072
	global_load_dwordx4 v[8:11], v[40:41], off offset:-2048
	global_load_dwordx4 v[4:7], v[40:41], off offset:-1024
	global_load_dwordx4 v[0:3], v[40:41], off
	s_load_dwordx2 s[2:3], s[6:7], 0xe8
	s_mov_b64 s[6:7], s[0:1]
	s_waitcnt lgkmcnt(0)
	v_lshl_add_u64 v[44:45], s[2:3], 0, v[24:25]
	v_add_co_u32_e32 v46, vcc, s8, v44
	s_waitcnt vmcnt(7)
	v_mul_f32_e32 v27, v29, v29
	v_mul_f32_e32 v48, v31, v31
	s_waitcnt vmcnt(6)
	v_mul_f32_e32 v49, v33, v33
	v_mul_f32_e32 v50, v35, v35
	s_waitcnt vmcnt(5)
	v_mul_f32_e32 v51, v37, v37
	v_mul_f32_e32 v52, v39, v39
	v_fmac_f32_e32 v27, v28, v28
	v_fmac_f32_e32 v48, v30, v30
	v_fmac_f32_e32 v49, v32, v32
	v_fmac_f32_e32 v50, v34, v34
	s_waitcnt vmcnt(4)
	v_mul_f32_e32 v53, v17, v17
	v_mul_f32_e32 v54, v19, v19
	v_fmac_f32_e32 v51, v36, v36
	v_fmac_f32_e32 v52, v38, v38
	v_add_f32_e32 v27, v27, v48
	v_add_f32_e32 v48, v49, v50
	v_fmac_f32_e32 v53, v16, v16
	v_fmac_f32_e32 v54, v18, v18
	v_add_f32_e32 v49, v51, v52
	v_add_f32_e32 v27, v27, v48
	v_add_f32_e32 v50, v53, v54
	v_add_f32_e32 v27, v27, v49
	v_add_f32_e32 v27, v27, v50
	v_addc_co_u32_e32 v47, vcc, -1, v45, vcc
	s_nop 0
	v_add_f32_dpp v27, v27, v27 row_ror:8 row_mask:0xf bank_mask:0xf bound_ctrl:1
	s_nop 1
	v_add_f32_dpp v27, v27, v27 row_ror:4 row_mask:0xf bank_mask:0xf bound_ctrl:1
	s_nop 1
	v_add_f32_dpp v27, v27, v27 row_ror:2 row_mask:0xf bank_mask:0xf bound_ctrl:1
	s_nop 1
	v_add_f32_dpp v27, v27, v27 row_ror:1 row_mask:0xf bank_mask:0xf bound_ctrl:1
	v_mov_b32_e32 v48, v27
	s_nop 1
	v_permlane16_swap_b32_e32 v27, v48
	v_add_f32_e32 v27, v27, v48
	v_mov_b32_e32 v48, v27
	s_nop 1
	v_permlane32_swap_b32_e32 v27, v48
	v_add_f32_e32 v27, v27, v48
	v_fmamk_f32 v27, v27, 0x3a800000, v21
	v_mul_f32_e32 v48, 0x4f800000, v27
	v_cmp_gt_f32_e32 vcc, s9, v27
	s_nop 1
	v_cndmask_b32_e32 v27, v27, v48, vcc
	v_sqrt_f32_e32 v48, v27
	s_nop 0
	v_add_u32_e32 v49, -1, v48
	v_add_u32_e32 v50, 1, v48
	v_fma_f32 v51, -v49, v48, v27
	v_fma_f32 v52, -v50, v48, v27
	v_cmp_ge_f32_e64 s[2:3], 0, v51
	s_nop 1
	v_cndmask_b32_e64 v48, v48, v49, s[2:3]
	v_cmp_lt_f32_e64 s[2:3], 0, v52
	s_nop 1
	v_cndmask_b32_e64 v48, v48, v50, s[2:3]
	v_mul_f32_e32 v49, 0x37800000, v48
	v_cndmask_b32_e32 v48, v48, v49, vcc
	v_cmp_class_f32_e32 vcc, v27, v26
	s_nop 1
	v_cndmask_b32_e32 v27, v48, v27, vcc
	v_div_scale_f32 v48, s[2:3], v27, v27, 1.0
	v_rcp_f32_e32 v50, v48
	v_div_scale_f32 v49, vcc, 1.0, v27, 1.0
	v_fma_f32 v51, -v48, v50, 1.0
	v_fmac_f32_e32 v50, v51, v50
	v_mul_f32_e32 v51, v49, v50
	v_fma_f32 v52, -v48, v51, v49
	v_fmac_f32_e32 v51, v52, v50
	v_fma_f32 v48, -v48, v51, v49
	v_div_fmas_f32 v48, v48, v50, v51
	v_div_fixup_f32 v48, v48, v27, 1.0
	v_pk_mul_f32 v[28:29], v[28:29], v[48:49] op_sel_hi:[1,0]
	v_pk_mul_f32 v[30:31], v[30:31], v[48:49] op_sel_hi:[1,0]
	s_waitcnt vmcnt(0)
; __device__ __forceinline__ float* kout() { return (float*)kin(29); }
; __device__ __forceinline__ float wave_sum(float v) { v = row16_allsum(v); v = rows_pair_sum(v); v = halves_pair_sum(v); return v; }
; __device__ __forceinline__ void final_norm(const Params& P, int gw, int NGW, int lane) {
;     ...
;         for (int q = 0; q < 2; ++q) {
; #pragma unroll
;             for (int j = 0; j < 4; ++j) s[q] += (v[q][j].x * v[q][j].x + v[q][j].y * v[q][j].y) + (v[q][j].z * v[q][j].z + v[q][j].w * v[q][j].w); }
; #pragma unroll
;         for (int q = 0; q < 2; ++q) {
;             f32x4* xr = (f32x4*)(kout() + (size_t)(m0 + q) * D) + lane;
;             const float rstd = 1.0f / sqrtf(wave_sum(s[q]) * (1.0f / D) + 1e-6f);
; #pragma unroll
;             for (int j = 0; j < 4; ++j) { const f32x4 gg = ((const f32x4*)g)[lane + 64 * j]; xr[64 * j] = v[q][j] * rstd * gg; }
	v_pk_mul_f32 v[28:29], v[60:61], v[28:29]
	v_pk_mul_f32 v[30:31], v[62:63], v[30:31]
	global_store_dwordx4 v[46:47], v[28:31], off offset:-3072
	s_nop 1
	v_pk_mul_f32 v[34:35], v[34:35], v[48:49] op_sel_hi:[1,0]
	v_pk_mul_f32 v[32:33], v[32:33], v[48:49] op_sel_hi:[1,0]
	v_pk_mul_f32 v[18:19], v[18:19], v[48:49] op_sel_hi:[1,0]
	v_pk_mul_f32 v[16:17], v[16:17], v[48:49] op_sel_hi:[1,0]
	v_mul_f32_e32 v27, v13, v13
	v_fmac_f32_e32 v27, v12, v12
	v_pk_mul_f32 v[28:29], v[64:65], v[32:33]
	v_pk_mul_f32 v[30:31], v[66:67], v[34:35]
	global_store_dwordx4 v[46:47], v[28:31], off offset:-2048
	s_nop 1
	v_pk_mul_f32 v[32:33], v[38:39], v[48:49] op_sel_hi:[1,0]
	v_pk_mul_f32 v[34:35], v[36:37], v[48:49] op_sel_hi:[1,0]
	v_pk_mul_f32 v[30:31], v[70:71], v[32:33]
	v_pk_mul_f32 v[28:29], v[68:69], v[34:35]
	global_store_dwordx4 v[46:47], v[28:31], off offset:-1024
	s_nop 1
	v_mul_f32_e32 v32, v15, v15
	v_mul_f32_e32 v33, v9, v9
	v_mul_f32_e32 v34, v11, v11
	v_mul_f32_e32 v35, v5, v5
	v_fmac_f32_e32 v32, v14, v14
	v_fmac_f32_e32 v33, v8, v8
	v_fmac_f32_e32 v34, v10, v10
	v_fmac_f32_e32 v35, v4, v4
	v_add_f32_e32 v27, v27, v32
	v_pk_mul_f32 v[16:17], v[72:73], v[16:17]
	v_pk_mul_f32 v[18:19], v[74:75], v[18:19]
	global_store_dwordx4 v[44:45], v[16:19], off offset:-4096
	s_nop 1
	v_mul_f32_e32 v28, v7, v7
	v_mul_f32_e32 v29, v1, v1
	v_mul_f32_e32 v30, v3, v3
	v_fmac_f32_e32 v28, v6, v6
	v_add_f32_e32 v31, v33, v34
	v_fmac_f32_e32 v29, v0, v0
	v_fmac_f32_e32 v30, v2, v2
	v_add_f32_e32 v28, v35, v28
	v_add_f32_e32 v27, v27, v31
	v_add_f32_e32 v29, v29, v30
	v_add_f32_e32 v27, v27, v28
	v_add_f32_e32 v27, v27, v29
	s_nop 1
	v_add_f32_dpp v27, v27, v27 row_ror:8 row_mask:0xf bank_mask:0xf bound_ctrl:1
	s_nop 1
	v_add_f32_dpp v27, v27, v27 row_ror:4 row_mask:0xf bank_mask:0xf bound_ctrl:1
	s_nop 1
	v_add_f32_dpp v27, v27, v27 row_ror:2 row_mask:0xf bank_mask:0xf bound_ctrl:1
	s_nop 1
	v_add_f32_dpp v27, v27, v27 row_ror:1 row_mask:0xf bank_mask:0xf bound_ctrl:1
	v_mov_b32_e32 v28, v27
	s_nop 1
	v_permlane16_swap_b32_e32 v27, v28
	v_add_f32_e32 v27, v27, v28
	v_mov_b32_e32 v28, v27
	s_nop 1
	v_permlane32_swap_b32_e32 v27, v28
	v_add_f32_e32 v27, v27, v28
	v_fmamk_f32 v27, v27, 0x3a800000, v21
	v_mul_f32_e32 v28, 0x4f800000, v27
	v_cmp_gt_f32_e32 vcc, s9, v27
	s_nop 1
	v_cndmask_b32_e32 v27, v27, v28, vcc
	v_sqrt_f32_e32 v28, v27
	s_nop 0
	v_add_u32_e32 v29, -1, v28
	v_add_u32_e32 v30, 1, v28
	v_fma_f32 v31, -v29, v28, v27
	v_fma_f32 v32, -v30, v28, v27
	v_cmp_ge_f32_e64 s[2:3], 0, v31
	s_nop 1
	v_cndmask_b32_e64 v28, v28, v29, s[2:3]
	v_cmp_lt_f32_e64 s[2:3], 0, v32
	s_nop 1
	v_cndmask_b32_e64 v28, v28, v30, s[2:3]
	v_mul_f32_e32 v29, 0x37800000, v28
	v_cndmask_b32_e32 v28, v28, v29, vcc
	v_cmp_class_f32_e32 vcc, v27, v26
	s_nop 1
	v_cndmask_b32_e32 v27, v28, v27, vcc
	v_div_scale_f32 v28, s[2:3], v27, v27, 1.0
	v_rcp_f32_e32 v30, v28
	v_div_scale_f32 v29, vcc, 1.0, v27, 1.0
	s_load_dwordx2 s[2:3], s[6:7], 0xe8
	v_fma_f32 v31, -v28, v30, 1.0
	v_fmac_f32_e32 v30, v31, v30
	v_mul_f32_e32 v31, v29, v30
	v_fma_f32 v32, -v28, v31, v29
	v_fmac_f32_e32 v31, v32, v30
	v_fma_f32 v28, -v28, v31, v29
	v_div_fmas_f32 v28, v28, v30, v31
	v_div_fixup_f32 v28, v28, v27, 1.0
	v_pk_mul_f32 v[14:15], v[14:15], v[28:29] op_sel_hi:[1,0]
	v_pk_mul_f32 v[12:13], v[12:13], v[28:29] op_sel_hi:[1,0]
	s_waitcnt lgkmcnt(0)
	v_lshl_add_u64 v[30:31], s[2:3], 0, v[24:25]
	v_pk_mul_f32 v[10:11], v[10:11], v[28:29] op_sel_hi:[1,0]
	v_pk_mul_f32 v[8:9], v[8:9], v[28:29] op_sel_hi:[1,0]
	v_pk_mul_f32 v[12:13], v[60:61], v[12:13]
	v_pk_mul_f32 v[14:15], v[62:63], v[14:15]
	global_store_dwordx4 v[30:31], v[12:15], off offset:-3072
	s_nop 1
	v_pk_mul_f32 v[6:7], v[6:7], v[28:29] op_sel_hi:[1,0]
	v_pk_mul_f32 v[4:5], v[4:5], v[28:29] op_sel_hi:[1,0]
	v_cmp_lt_i32_e32 vcc, s10, v20
	v_pk_mul_f32 v[2:3], v[2:3], v[28:29] op_sel_hi:[1,0]
	v_pk_mul_f32 v[0:1], v[0:1], v[28:29] op_sel_hi:[1,0]
	s_or_b64 s[4:5], vcc, s[4:5]
	v_lshl_add_u64 v[24:25], v[24:25], 0, s[12:13]
	v_pk_mul_f32 v[8:9], v[64:65], v[8:9]
	v_pk_mul_f32 v[10:11], v[66:67], v[10:11]
	global_store_dwordx4 v[30:31], v[8:11], off offset:-2048
	s_nop 1
	v_pk_mul_f32 v[4:5], v[68:69], v[4:5]
	v_pk_mul_f32 v[6:7], v[70:71], v[6:7]
	global_store_dwordx4 v[30:31], v[4:7], off offset:-1024
	s_nop 1
	v_pk_mul_f32 v[0:1], v[72:73], v[0:1]
	v_pk_mul_f32 v[2:3], v[74:75], v[2:3]
	global_store_dwordx4 v[30:31], v[0:3], off
	s_nop 1
	s_andn2_b64 exec, exec, s[4:5]
	s_cbranch_execnz .LBB0_1108
